# GEMM main loops: MFMAs of each 8-group reordered (serpentine) so consecutive MFMAs always share one operand register; bit-identical results
# speedup vs baseline: 1.0062x; 1.0004x over previous
.LBB0_202:
	ds_read_b128 v[112:115], v218
	ds_read_b128 v[116:119], v218 offset:1024
	ds_read_b128 v[120:123], v218 offset:2048
	ds_read_b128 v[124:127], v218 offset:3072
	s_waitcnt vmcnt(0)
	ds_read_b128 v[128:131], v219
	ds_read_b128 v[132:135], v219 offset:1024
	ds_read_b128 v[136:139], v219 offset:2048
	ds_read_b128 v[140:143], v219 offset:3072
	s_add_u32 s69, s12, 0xfffc0080
	s_addc_u32 s73, s13, -1
	s_cmp_eq_u32 s68, 12
	s_cselect_b32 s83, s1, s73
	s_cselect_b32 s82, s2, s69
	s_cselect_b32 s81, s3, s66
	s_cselect_b32 s80, s34, s35
	v_lshl_add_u64 v[230:231], s[12:13], 0, v[192:193]
	s_add_i32 m0, s15, 0xc000
	ds_read_b128 v[152:155], v220
	ds_read_b128 v[156:159], v220 offset:1024
	ds_read_b128 v[160:163], v220 offset:2048
	ds_read_b128 v[164:167], v220 offset:3072
	ds_read_b128 v[200:203], v220 offset:4096
	ds_read_b128 v[204:207], v220 offset:5120
	ds_read_b128 v[208:211], v220 offset:6144
	ds_read_b128 v[226:229], v220 offset:7168
	global_load_lds_dwordx4 v[230:231], off
	v_lshl_add_u64 v[230:231], s[12:13], 0, v[194:195]
	s_add_i32 m0, s15, 0xe000
	s_nop 0
	global_load_lds_dwordx4 v[230:231], off
	s_waitcnt vmcnt(8)
	s_waitcnt lgkmcnt(0)
	s_barrier
	s_setprio 1
	s_waitcnt lgkmcnt(0)
	v_mfma_f32_16x16x32_bf16 v[172:175], v[112:115], v[152:155], v[172:175]
	v_mfma_f32_16x16x32_bf16 v[168:171], v[120:123], v[152:155], v[168:171]
	v_mfma_f32_16x16x32_bf16 v[104:107], v[120:123], v[160:163], v[104:107]
	v_mfma_f32_16x16x32_bf16 v[108:111], v[112:115], v[160:163], v[108:111]
	v_mfma_f32_16x16x32_bf16 v[92:95], v[112:115], v[200:203], v[92:95]
	v_mfma_f32_16x16x32_bf16 v[88:91], v[120:123], v[200:203], v[88:91]
	v_mfma_f32_16x16x32_bf16 v[72:75], v[120:123], v[208:211], v[72:75]
	v_mfma_f32_16x16x32_bf16 v[76:79], v[112:115], v[208:211], v[76:79]
	v_mfma_f32_16x16x32_bf16 v[172:175], v[116:119], v[156:159], v[172:175]
	v_mfma_f32_16x16x32_bf16 v[168:171], v[124:127], v[156:159], v[168:171]
	v_mfma_f32_16x16x32_bf16 v[104:107], v[124:127], v[164:167], v[104:107]
	v_mfma_f32_16x16x32_bf16 v[108:111], v[116:119], v[164:167], v[108:111]
	v_mfma_f32_16x16x32_bf16 v[92:95], v[116:119], v[204:207], v[92:95]
	v_mfma_f32_16x16x32_bf16 v[88:91], v[124:127], v[204:207], v[88:91]
	v_mfma_f32_16x16x32_bf16 v[72:75], v[124:127], v[226:229], v[72:75]
	v_mfma_f32_16x16x32_bf16 v[76:79], v[116:119], v[226:229], v[76:79]
	s_setprio 0
	s_setprio 1
	v_mfma_f32_16x16x32_bf16 v[148:151], v[128:131], v[152:155], v[148:151]
	v_mfma_f32_16x16x32_bf16 v[144:147], v[136:139], v[152:155], v[144:147]
	v_mfma_f32_16x16x32_bf16 v[96:99], v[136:139], v[160:163], v[96:99]
	v_mfma_f32_16x16x32_bf16 v[100:103], v[128:131], v[160:163], v[100:103]
	v_mfma_f32_16x16x32_bf16 v[84:87], v[128:131], v[200:203], v[84:87]
	v_mfma_f32_16x16x32_bf16 v[80:83], v[136:139], v[200:203], v[80:83]
	v_mfma_f32_16x16x32_bf16 v[64:67], v[136:139], v[208:211], v[64:67]
	v_mfma_f32_16x16x32_bf16 v[68:71], v[128:131], v[208:211], v[68:71]
	v_mfma_f32_16x16x32_bf16 v[148:151], v[132:135], v[156:159], v[148:151]
	v_mfma_f32_16x16x32_bf16 v[144:147], v[140:143], v[156:159], v[144:147]
	v_mfma_f32_16x16x32_bf16 v[96:99], v[140:143], v[164:167], v[96:99]
	v_mfma_f32_16x16x32_bf16 v[100:103], v[132:135], v[164:167], v[100:103]
	v_mfma_f32_16x16x32_bf16 v[84:87], v[132:135], v[204:207], v[84:87]
	v_mfma_f32_16x16x32_bf16 v[80:83], v[140:143], v[204:207], v[80:83]
	v_mfma_f32_16x16x32_bf16 v[64:67], v[140:143], v[226:229], v[64:67]
	v_mfma_f32_16x16x32_bf16 v[68:71], v[132:135], v[226:229], v[68:71]
	s_setprio 0
	s_barrier
	s_add_i32 s69, s59, s14
	v_lshl_add_u64 v[230:231], s[80:81], 0, v[178:179]
	s_mov_b32 m0, s69
	ds_read_b128 v[152:155], v220 offset:16384
	ds_read_b128 v[156:159], v220 offset:17408
	ds_read_b128 v[160:163], v220 offset:18432
	ds_read_b128 v[164:167], v220 offset:19456
	ds_read_b128 v[200:203], v220 offset:20480
	ds_read_b128 v[204:207], v220 offset:21504
	ds_read_b128 v[208:211], v220 offset:22528
	ds_read_b128 v[226:229], v220 offset:23552
	global_load_lds_dwordx4 v[230:231], off
	s_add_i32 m0, s69, 0x2000
	s_add_u32 s86, s80, 0x40000
	v_lshl_add_u64 v[232:233], s[80:81], 0, v[182:183]
	s_addc_u32 s87, s81, 0
	s_add_i32 s69, s65, s14
	global_load_lds_dwordx4 v[232:233], off
	v_lshl_add_u64 v[234:235], s[86:87], 0, v[178:179]
	s_mov_b32 m0, s69
	v_lshl_add_u64 v[236:237], s[82:83], 0, v[180:181]
	global_load_lds_dwordx4 v[234:235], off
	v_lshl_add_u64 v[234:235], s[86:87], 0, v[182:183]
	s_add_i32 m0, s69, 0x2000
	s_nop 0
	global_load_lds_dwordx4 v[234:235], off
	v_lshl_add_u64 v[234:235], s[82:83], 0, v[176:177]
	s_mov_b32 m0, s15
	s_nop 0
	global_load_lds_dwordx4 v[234:235], off
	s_mov_b32 m0, s52
	s_nop 0
	global_load_lds_dwordx4 v[236:237], off
	s_waitcnt vmcnt(8)
	s_waitcnt lgkmcnt(0)
	s_barrier
	s_setprio 1
	s_waitcnt lgkmcnt(0)
	v_mfma_f32_16x16x32_bf16 v[60:63], v[112:115], v[152:155], v[60:63]
	v_mfma_f32_16x16x32_bf16 v[56:59], v[120:123], v[152:155], v[56:59]
	v_mfma_f32_16x16x32_bf16 v[40:43], v[120:123], v[160:163], v[40:43]
	v_mfma_f32_16x16x32_bf16 v[44:47], v[112:115], v[160:163], v[44:47]
	v_mfma_f32_16x16x32_bf16 v[28:31], v[112:115], v[200:203], v[28:31]
	v_mfma_f32_16x16x32_bf16 v[24:27], v[120:123], v[200:203], v[24:27]
	v_mfma_f32_16x16x32_bf16 v[8:11], v[120:123], v[208:211], v[8:11]
	v_mfma_f32_16x16x32_bf16 v[12:15], v[112:115], v[208:211], v[12:15]
	v_mfma_f32_16x16x32_bf16 v[60:63], v[116:119], v[156:159], v[60:63]
	v_mfma_f32_16x16x32_bf16 v[56:59], v[124:127], v[156:159], v[56:59]
	v_mfma_f32_16x16x32_bf16 v[40:43], v[124:127], v[164:167], v[40:43]
	v_mfma_f32_16x16x32_bf16 v[44:47], v[116:119], v[164:167], v[44:47]
	v_mfma_f32_16x16x32_bf16 v[28:31], v[116:119], v[204:207], v[28:31]
	v_mfma_f32_16x16x32_bf16 v[24:27], v[124:127], v[204:207], v[24:27]
	v_mfma_f32_16x16x32_bf16 v[8:11], v[124:127], v[226:229], v[8:11]
	v_mfma_f32_16x16x32_bf16 v[12:15], v[116:119], v[226:229], v[12:15]
	s_setprio 0
	s_setprio 1
	v_mfma_f32_16x16x32_bf16 v[52:55], v[128:131], v[152:155], v[52:55]
	v_mfma_f32_16x16x32_bf16 v[48:51], v[136:139], v[152:155], v[48:51]
	v_mfma_f32_16x16x32_bf16 v[32:35], v[136:139], v[160:163], v[32:35]
	v_mfma_f32_16x16x32_bf16 v[36:39], v[128:131], v[160:163], v[36:39]
	v_mfma_f32_16x16x32_bf16 v[20:23], v[128:131], v[200:203], v[20:23]
	v_mfma_f32_16x16x32_bf16 v[16:19], v[136:139], v[200:203], v[16:19]
	v_mfma_f32_16x16x32_bf16 v[0:3], v[136:139], v[208:211], v[0:3]
	v_mfma_f32_16x16x32_bf16 v[4:7], v[128:131], v[208:211], v[4:7]
	v_mfma_f32_16x16x32_bf16 v[52:55], v[132:135], v[156:159], v[52:55]
	v_mfma_f32_16x16x32_bf16 v[48:51], v[140:143], v[156:159], v[48:51]
	v_mfma_f32_16x16x32_bf16 v[32:35], v[140:143], v[164:167], v[32:35]
	v_mfma_f32_16x16x32_bf16 v[36:39], v[132:135], v[164:167], v[36:39]
	v_mfma_f32_16x16x32_bf16 v[20:23], v[132:135], v[204:207], v[20:23]
	v_mfma_f32_16x16x32_bf16 v[16:19], v[140:143], v[204:207], v[16:19]
	v_mfma_f32_16x16x32_bf16 v[0:3], v[140:143], v[226:229], v[0:3]
	v_mfma_f32_16x16x32_bf16 v[4:7], v[132:135], v[226:229], v[4:7]
	s_setprio 0
	s_barrier
	s_add_i32 s69, 0, 0x18000
	s_add_i32 s73, 0, 0x1c000
	v_add_u32_e32 v124, s69, v212
	v_add_u32_e32 v140, s73, v212
	ds_read_b128 v[112:115], v124
	ds_read_b128 v[116:119], v124 offset:1024
	ds_read_b128 v[120:123], v124 offset:2048
	ds_read_b128 v[124:127], v124 offset:3072
	ds_read_b128 v[128:131], v140
	ds_read_b128 v[132:135], v140 offset:1024
	ds_read_b128 v[136:139], v140 offset:2048
	ds_read_b128 v[140:143], v140 offset:3072
	s_add_u32 s82, s82, 0x40000
	s_addc_u32 s83, s83, 0
	s_mov_b32 m0, s53
	v_lshl_add_u64 v[238:239], s[82:83], 0, v[176:177]
	ds_read_b128 v[152:155], v220 offset:32768
	ds_read_b128 v[156:159], v220 offset:33792
	ds_read_b128 v[160:163], v220 offset:34816
	ds_read_b128 v[164:167], v220 offset:35840
	ds_read_b128 v[200:203], v220 offset:36864
	ds_read_b128 v[204:207], v220 offset:37888
	ds_read_b128 v[208:211], v220 offset:38912
	ds_read_b128 v[226:229], v220 offset:39936
	global_load_lds_dwordx4 v[238:239], off
	v_lshl_add_u64 v[238:239], s[82:83], 0, v[180:181]
	s_mov_b32 m0, s54
	s_nop 0
	global_load_lds_dwordx4 v[238:239], off
	s_waitcnt vmcnt(8)
	s_waitcnt lgkmcnt(0)
	s_barrier
	s_setprio 1
	s_waitcnt lgkmcnt(0)
	v_mfma_f32_16x16x32_bf16 v[172:175], v[112:115], v[152:155], v[172:175]
	v_mfma_f32_16x16x32_bf16 v[168:171], v[120:123], v[152:155], v[168:171]
	v_mfma_f32_16x16x32_bf16 v[104:107], v[120:123], v[160:163], v[104:107]
	v_mfma_f32_16x16x32_bf16 v[108:111], v[112:115], v[160:163], v[108:111]
	v_mfma_f32_16x16x32_bf16 v[92:95], v[112:115], v[200:203], v[92:95]
	v_mfma_f32_16x16x32_bf16 v[88:91], v[120:123], v[200:203], v[88:91]
	v_mfma_f32_16x16x32_bf16 v[72:75], v[120:123], v[208:211], v[72:75]
	v_mfma_f32_16x16x32_bf16 v[76:79], v[112:115], v[208:211], v[76:79]
	v_mfma_f32_16x16x32_bf16 v[172:175], v[116:119], v[156:159], v[172:175]
	v_mfma_f32_16x16x32_bf16 v[168:171], v[124:127], v[156:159], v[168:171]
	v_mfma_f32_16x16x32_bf16 v[104:107], v[124:127], v[164:167], v[104:107]
	v_mfma_f32_16x16x32_bf16 v[108:111], v[116:119], v[164:167], v[108:111]
	v_mfma_f32_16x16x32_bf16 v[92:95], v[116:119], v[204:207], v[92:95]
	v_mfma_f32_16x16x32_bf16 v[88:91], v[124:127], v[204:207], v[88:91]
	v_mfma_f32_16x16x32_bf16 v[72:75], v[124:127], v[226:229], v[72:75]
	v_mfma_f32_16x16x32_bf16 v[76:79], v[116:119], v[226:229], v[76:79]
	s_setprio 0
	s_setprio 1
	v_mfma_f32_16x16x32_bf16 v[148:151], v[128:131], v[152:155], v[148:151]
	v_mfma_f32_16x16x32_bf16 v[144:147], v[136:139], v[152:155], v[144:147]
	v_mfma_f32_16x16x32_bf16 v[96:99], v[136:139], v[160:163], v[96:99]
	v_mfma_f32_16x16x32_bf16 v[100:103], v[128:131], v[160:163], v[100:103]
	v_mfma_f32_16x16x32_bf16 v[84:87], v[128:131], v[200:203], v[84:87]
	v_mfma_f32_16x16x32_bf16 v[80:83], v[136:139], v[200:203], v[80:83]
	v_mfma_f32_16x16x32_bf16 v[64:67], v[136:139], v[208:211], v[64:67]
	v_mfma_f32_16x16x32_bf16 v[68:71], v[128:131], v[208:211], v[68:71]
	v_mfma_f32_16x16x32_bf16 v[148:151], v[132:135], v[156:159], v[148:151]
	v_mfma_f32_16x16x32_bf16 v[144:147], v[140:143], v[156:159], v[144:147]
	v_mfma_f32_16x16x32_bf16 v[96:99], v[140:143], v[164:167], v[96:99]
	v_mfma_f32_16x16x32_bf16 v[100:103], v[132:135], v[164:167], v[100:103]
	v_mfma_f32_16x16x32_bf16 v[84:87], v[132:135], v[204:207], v[84:87]
	v_mfma_f32_16x16x32_bf16 v[80:83], v[140:143], v[204:207], v[80:83]
	v_mfma_f32_16x16x32_bf16 v[64:67], v[140:143], v[226:229], v[64:67]
	v_mfma_f32_16x16x32_bf16 v[68:71], v[132:135], v[226:229], v[68:71]
	s_setprio 0
	s_barrier
	s_add_i32 s69, s69, s14
	v_lshl_add_u64 v[230:231], v[230:231], 0, s[40:41]
	s_mov_b32 m0, s69
	ds_read_b128 v[152:155], v220 offset:49152
	ds_read_b128 v[156:159], v220 offset:50176
	ds_read_b128 v[160:163], v220 offset:51200
	ds_read_b128 v[164:167], v220 offset:52224
	ds_read_b128 v[200:203], v220 offset:53248
	ds_read_b128 v[204:207], v220 offset:54272
	ds_read_b128 v[208:211], v220 offset:55296
	ds_read_b128 v[226:229], v220 offset:56320
	global_load_lds_dwordx4 v[230:231], off
	s_add_i32 m0, s69, 0x2000
	s_add_u32 s80, s80, 0x40080
	v_lshl_add_u64 v[230:231], v[232:233], 0, s[40:41]
	s_addc_u32 s81, s81, 0
	s_add_i32 s69, s73, s14
	global_load_lds_dwordx4 v[230:231], off
	v_lshl_add_u64 v[230:231], s[80:81], 0, v[178:179]
	s_mov_b32 m0, s69
	s_nop 0
	global_load_lds_dwordx4 v[230:231], off
	v_lshl_add_u64 v[230:231], s[80:81], 0, v[182:183]
	s_add_i32 m0, s69, 0x2000
	s_nop 0
	global_load_lds_dwordx4 v[230:231], off
	v_lshl_add_u64 v[230:231], v[234:235], 0, s[40:41]
	s_mov_b32 m0, s57
	s_nop 0
	global_load_lds_dwordx4 v[230:231], off
	v_lshl_add_u64 v[230:231], v[236:237], 0, s[40:41]
	s_mov_b32 m0, s58
	s_nop 0
	global_load_lds_dwordx4 v[230:231], off
	s_waitcnt vmcnt(8)
	s_waitcnt lgkmcnt(0)
	s_barrier
	s_setprio 1
	s_waitcnt lgkmcnt(0)
	v_mfma_f32_16x16x32_bf16 v[60:63], v[112:115], v[152:155], v[60:63]
	v_mfma_f32_16x16x32_bf16 v[56:59], v[120:123], v[152:155], v[56:59]
	v_mfma_f32_16x16x32_bf16 v[40:43], v[120:123], v[160:163], v[40:43]
	v_mfma_f32_16x16x32_bf16 v[44:47], v[112:115], v[160:163], v[44:47]
	v_mfma_f32_16x16x32_bf16 v[28:31], v[112:115], v[200:203], v[28:31]
	v_mfma_f32_16x16x32_bf16 v[24:27], v[120:123], v[200:203], v[24:27]
	v_mfma_f32_16x16x32_bf16 v[8:11], v[120:123], v[208:211], v[8:11]
	v_mfma_f32_16x16x32_bf16 v[12:15], v[112:115], v[208:211], v[12:15]
	v_mfma_f32_16x16x32_bf16 v[60:63], v[116:119], v[156:159], v[60:63]
	v_mfma_f32_16x16x32_bf16 v[56:59], v[124:127], v[156:159], v[56:59]
	v_mfma_f32_16x16x32_bf16 v[40:43], v[124:127], v[164:167], v[40:43]
	v_mfma_f32_16x16x32_bf16 v[44:47], v[116:119], v[164:167], v[44:47]
	v_mfma_f32_16x16x32_bf16 v[28:31], v[116:119], v[204:207], v[28:31]
	v_mfma_f32_16x16x32_bf16 v[24:27], v[124:127], v[204:207], v[24:27]
	v_mfma_f32_16x16x32_bf16 v[8:11], v[124:127], v[226:229], v[8:11]
	v_mfma_f32_16x16x32_bf16 v[12:15], v[116:119], v[226:229], v[12:15]
	s_setprio 0
	s_setprio 1
	v_mfma_f32_16x16x32_bf16 v[52:55], v[128:131], v[152:155], v[52:55]
	v_mfma_f32_16x16x32_bf16 v[48:51], v[136:139], v[152:155], v[48:51]
	v_mfma_f32_16x16x32_bf16 v[32:35], v[136:139], v[160:163], v[32:35]
	v_mfma_f32_16x16x32_bf16 v[36:39], v[128:131], v[160:163], v[36:39]
	v_mfma_f32_16x16x32_bf16 v[20:23], v[128:131], v[200:203], v[20:23]
	v_mfma_f32_16x16x32_bf16 v[16:19], v[136:139], v[200:203], v[16:19]
	v_mfma_f32_16x16x32_bf16 v[0:3], v[136:139], v[208:211], v[0:3]
	v_mfma_f32_16x16x32_bf16 v[4:7], v[128:131], v[208:211], v[4:7]
	v_mfma_f32_16x16x32_bf16 v[52:55], v[132:135], v[156:159], v[52:55]
	v_mfma_f32_16x16x32_bf16 v[48:51], v[140:143], v[156:159], v[48:51]
	v_mfma_f32_16x16x32_bf16 v[32:35], v[140:143], v[164:167], v[32:35]
	v_mfma_f32_16x16x32_bf16 v[36:39], v[132:135], v[164:167], v[36:39]
	v_mfma_f32_16x16x32_bf16 v[20:23], v[132:135], v[204:207], v[20:23]
	v_mfma_f32_16x16x32_bf16 v[16:19], v[140:143], v[204:207], v[16:19]
	v_mfma_f32_16x16x32_bf16 v[0:3], v[140:143], v[226:229], v[0:3]
	v_mfma_f32_16x16x32_bf16 v[4:7], v[132:135], v[226:229], v[4:7]
	s_setprio 0
	s_barrier
	s_add_i32 s68, s68, 2
	s_add_u32 s12, s12, 0x100
	s_addc_u32 s13, s13, 0
	s_add_u32 s35, s35, 0x100
	s_addc_u32 s66, s66, 0
	s_cmp_gt_u32 s68, 13
	s_cbranch_scc0 .LBB0_202
	s_and_b64 vcc, exec, s[42:43]
	s_cbranch_vccz .LBB0_205
	s_barrier

.LBB0_646:
	ds_read_b128 v[88:91], v236
	ds_read_b128 v[100:103], v236 offset:1024
	ds_read_b128 v[112:115], v236 offset:2048
	ds_read_b128 v[124:127], v236 offset:3072
	ds_read_b128 v[136:139], v237
	ds_read_b128 v[148:151], v237 offset:1024
	ds_read_b128 v[152:155], v237 offset:2048
	ds_read_b128 v[156:159], v237 offset:3072
	s_add_u32 s44, s42, 0xfffc0080
	s_addc_u32 s45, s43, -1
	s_cmp_eq_u32 s57, 12
	s_cselect_b32 s47, s31, s45
	s_cselect_b32 s46, s41, s44
	s_cselect_b32 s45, s29, s56
	s_cselect_b32 s44, s54, s55
	v_lshl_add_u64 v[208:209], s[42:43], 0, v[194:195]
	s_add_i32 m0, s3, 0xc000
	ds_read_b128 v[160:163], v238
	ds_read_b128 v[164:167], v238 offset:1024
	ds_read_b128 v[168:171], v238 offset:2048
	ds_read_b128 v[172:175], v238 offset:3072
	ds_read_b128 v[176:179], v238 offset:4096
	ds_read_b128 v[180:183], v238 offset:5120
	ds_read_b128 v[202:205], v238 offset:6144
	ds_read_b128 v[228:231], v238 offset:7168
	global_load_lds_dwordx4 v[208:209], off
	v_lshl_add_u64 v[208:209], s[42:43], 0, v[196:197]
	s_add_i32 m0, s3, 0xe000
	s_nop 0
	global_load_lds_dwordx4 v[208:209], off
	s_waitcnt vmcnt(8)
	s_waitcnt lgkmcnt(0)
	s_barrier
	s_setprio 1
	s_waitcnt lgkmcnt(0)
	v_mfma_f32_16x16x32_bf16 v[144:147], v[88:91], v[160:163], v[144:147]
	v_mfma_f32_16x16x32_bf16 v[140:143], v[112:115], v[160:163], v[140:143]
	v_mfma_f32_16x16x32_bf16 v[116:119], v[112:115], v[168:171], v[116:119]
	v_mfma_f32_16x16x32_bf16 v[120:123], v[88:91], v[168:171], v[120:123]
	v_mfma_f32_16x16x32_bf16 v[96:99], v[88:91], v[176:179], v[96:99]
	v_mfma_f32_16x16x32_bf16 v[92:95], v[112:115], v[176:179], v[92:95]
	v_mfma_f32_16x16x32_bf16 v[72:75], v[112:115], v[202:205], v[72:75]
	v_mfma_f32_16x16x32_bf16 v[76:79], v[88:91], v[202:205], v[76:79]
	v_mfma_f32_16x16x32_bf16 v[144:147], v[100:103], v[164:167], v[144:147]
	v_mfma_f32_16x16x32_bf16 v[140:143], v[124:127], v[164:167], v[140:143]
	v_mfma_f32_16x16x32_bf16 v[116:119], v[124:127], v[172:175], v[116:119]
	v_mfma_f32_16x16x32_bf16 v[120:123], v[100:103], v[172:175], v[120:123]
	v_mfma_f32_16x16x32_bf16 v[96:99], v[100:103], v[180:183], v[96:99]
	v_mfma_f32_16x16x32_bf16 v[92:95], v[124:127], v[180:183], v[92:95]
	v_mfma_f32_16x16x32_bf16 v[72:75], v[124:127], v[228:231], v[72:75]
	v_mfma_f32_16x16x32_bf16 v[76:79], v[100:103], v[228:231], v[76:79]
	s_setprio 0
	s_setprio 1
	v_mfma_f32_16x16x32_bf16 v[132:135], v[136:139], v[160:163], v[132:135]
	v_mfma_f32_16x16x32_bf16 v[128:131], v[152:155], v[160:163], v[128:131]
	v_mfma_f32_16x16x32_bf16 v[104:107], v[152:155], v[168:171], v[104:107]
	v_mfma_f32_16x16x32_bf16 v[108:111], v[136:139], v[168:171], v[108:111]
	v_mfma_f32_16x16x32_bf16 v[84:87], v[136:139], v[176:179], v[84:87]
	v_mfma_f32_16x16x32_bf16 v[80:83], v[152:155], v[176:179], v[80:83]
	v_mfma_f32_16x16x32_bf16 v[64:67], v[152:155], v[202:205], v[64:67]
	v_mfma_f32_16x16x32_bf16 v[68:71], v[136:139], v[202:205], v[68:71]
	v_mfma_f32_16x16x32_bf16 v[132:135], v[148:151], v[164:167], v[132:135]
	v_mfma_f32_16x16x32_bf16 v[128:131], v[156:159], v[164:167], v[128:131]
	v_mfma_f32_16x16x32_bf16 v[104:107], v[156:159], v[172:175], v[104:107]
	v_mfma_f32_16x16x32_bf16 v[108:111], v[148:151], v[172:175], v[108:111]
	v_mfma_f32_16x16x32_bf16 v[84:87], v[148:151], v[180:183], v[84:87]
	v_mfma_f32_16x16x32_bf16 v[80:83], v[156:159], v[180:183], v[80:83]
	v_mfma_f32_16x16x32_bf16 v[64:67], v[156:159], v[228:231], v[64:67]
	v_mfma_f32_16x16x32_bf16 v[68:71], v[148:151], v[228:231], v[68:71]
	s_setprio 0
	s_barrier
	s_add_i32 s58, s51, s2
	v_lshl_add_u64 v[208:209], s[44:45], 0, v[186:187]
	s_mov_b32 m0, s58
	ds_read_b128 v[160:163], v238 offset:16384
	ds_read_b128 v[164:167], v238 offset:17408
	ds_read_b128 v[168:171], v238 offset:18432
	ds_read_b128 v[172:175], v238 offset:19456
	ds_read_b128 v[176:179], v238 offset:20480
	ds_read_b128 v[180:183], v238 offset:21504
	ds_read_b128 v[202:205], v238 offset:22528
	ds_read_b128 v[228:231], v238 offset:23552
	global_load_lds_dwordx4 v[208:209], off
	s_add_i32 m0, s58, 0x2000
	s_add_u32 s58, s44, 0x40000
	v_lshl_add_u64 v[212:213], s[44:45], 0, v[190:191]
	s_addc_u32 s59, s45, 0
	s_add_i32 s64, s52, s2
	global_load_lds_dwordx4 v[212:213], off
	v_lshl_add_u64 v[216:217], s[58:59], 0, v[186:187]
	s_mov_b32 m0, s64
	v_lshl_add_u64 v[220:221], s[46:47], 0, v[188:189]
	global_load_lds_dwordx4 v[216:217], off
	v_lshl_add_u64 v[216:217], s[58:59], 0, v[190:191]
	s_add_i32 m0, s64, 0x2000
	s_nop 0
	global_load_lds_dwordx4 v[216:217], off
	v_lshl_add_u64 v[216:217], s[46:47], 0, v[184:185]
	s_mov_b32 m0, s3
	s_nop 0
	global_load_lds_dwordx4 v[216:217], off
	s_mov_b32 m0, s33
	s_nop 0
	global_load_lds_dwordx4 v[220:221], off
	s_waitcnt vmcnt(8)
	s_waitcnt lgkmcnt(0)
	s_barrier
	s_setprio 1
	s_waitcnt lgkmcnt(0)
	v_mfma_f32_16x16x32_bf16 v[60:63], v[88:91], v[160:163], v[60:63]
	v_mfma_f32_16x16x32_bf16 v[56:59], v[112:115], v[160:163], v[56:59]
	v_mfma_f32_16x16x32_bf16 v[40:43], v[112:115], v[168:171], v[40:43]
	v_mfma_f32_16x16x32_bf16 v[44:47], v[88:91], v[168:171], v[44:47]
	v_mfma_f32_16x16x32_bf16 v[28:31], v[88:91], v[176:179], v[28:31]
	v_mfma_f32_16x16x32_bf16 v[24:27], v[112:115], v[176:179], v[24:27]
	v_mfma_f32_16x16x32_bf16 v[8:11], v[112:115], v[202:205], v[8:11]
	v_mfma_f32_16x16x32_bf16 v[12:15], v[88:91], v[202:205], v[12:15]
	v_mfma_f32_16x16x32_bf16 v[60:63], v[100:103], v[164:167], v[60:63]
	v_mfma_f32_16x16x32_bf16 v[56:59], v[124:127], v[164:167], v[56:59]
	v_mfma_f32_16x16x32_bf16 v[40:43], v[124:127], v[172:175], v[40:43]
	v_mfma_f32_16x16x32_bf16 v[44:47], v[100:103], v[172:175], v[44:47]
	v_mfma_f32_16x16x32_bf16 v[28:31], v[100:103], v[180:183], v[28:31]
	v_mfma_f32_16x16x32_bf16 v[24:27], v[124:127], v[180:183], v[24:27]
	v_mfma_f32_16x16x32_bf16 v[8:11], v[124:127], v[228:231], v[8:11]
	v_mfma_f32_16x16x32_bf16 v[12:15], v[100:103], v[228:231], v[12:15]
	s_setprio 0
	s_setprio 1
	v_mfma_f32_16x16x32_bf16 v[52:55], v[136:139], v[160:163], v[52:55]
	v_mfma_f32_16x16x32_bf16 v[48:51], v[152:155], v[160:163], v[48:51]
	v_mfma_f32_16x16x32_bf16 v[32:35], v[152:155], v[168:171], v[32:35]
	v_mfma_f32_16x16x32_bf16 v[36:39], v[136:139], v[168:171], v[36:39]
	v_mfma_f32_16x16x32_bf16 v[20:23], v[136:139], v[176:179], v[20:23]
	v_mfma_f32_16x16x32_bf16 v[16:19], v[152:155], v[176:179], v[16:19]
	v_mfma_f32_16x16x32_bf16 v[0:3], v[152:155], v[202:205], v[0:3]
	v_mfma_f32_16x16x32_bf16 v[4:7], v[136:139], v[202:205], v[4:7]
	v_mfma_f32_16x16x32_bf16 v[52:55], v[148:151], v[164:167], v[52:55]
	v_mfma_f32_16x16x32_bf16 v[48:51], v[156:159], v[164:167], v[48:51]
	v_mfma_f32_16x16x32_bf16 v[32:35], v[156:159], v[172:175], v[32:35]
	v_mfma_f32_16x16x32_bf16 v[36:39], v[148:151], v[172:175], v[36:39]
	v_mfma_f32_16x16x32_bf16 v[20:23], v[148:151], v[180:183], v[20:23]
	v_mfma_f32_16x16x32_bf16 v[16:19], v[156:159], v[180:183], v[16:19]
	v_mfma_f32_16x16x32_bf16 v[0:3], v[156:159], v[228:231], v[0:3]
	v_mfma_f32_16x16x32_bf16 v[4:7], v[148:151], v[228:231], v[4:7]
	s_setprio 0
	s_barrier
	s_add_i32 s58, 0, 0x18000
	s_add_i32 s59, 0, 0x1c000
	v_add_u32_e32 v124, s58, v211
	v_add_u32_e32 v156, s59, v211
	ds_read_b128 v[88:91], v124
	ds_read_b128 v[100:103], v124 offset:1024
	ds_read_b128 v[112:115], v124 offset:2048
	ds_read_b128 v[124:127], v124 offset:3072
	ds_read_b128 v[136:139], v156
	ds_read_b128 v[148:151], v156 offset:1024
	ds_read_b128 v[152:155], v156 offset:2048
	ds_read_b128 v[156:159], v156 offset:3072
	s_add_u32 s46, s46, 0x40000
	s_addc_u32 s47, s47, 0
	s_mov_b32 m0, s34
	v_lshl_add_u64 v[224:225], s[46:47], 0, v[184:185]
	ds_read_b128 v[160:163], v238 offset:32768
	ds_read_b128 v[164:167], v238 offset:33792
	ds_read_b128 v[168:171], v238 offset:34816
	ds_read_b128 v[172:175], v238 offset:35840
	ds_read_b128 v[176:179], v238 offset:36864
	ds_read_b128 v[180:183], v238 offset:37888
	ds_read_b128 v[202:205], v238 offset:38912
	ds_read_b128 v[228:231], v238 offset:39936
	global_load_lds_dwordx4 v[224:225], off
	v_lshl_add_u64 v[224:225], s[46:47], 0, v[188:189]
	s_mov_b32 m0, s35
	s_nop 0
	global_load_lds_dwordx4 v[224:225], off
	s_waitcnt vmcnt(8)
	s_waitcnt lgkmcnt(0)
	s_barrier
	s_setprio 1
	s_waitcnt lgkmcnt(0)
	v_mfma_f32_16x16x32_bf16 v[144:147], v[88:91], v[160:163], v[144:147]
	v_mfma_f32_16x16x32_bf16 v[140:143], v[112:115], v[160:163], v[140:143]
	v_mfma_f32_16x16x32_bf16 v[116:119], v[112:115], v[168:171], v[116:119]
	v_mfma_f32_16x16x32_bf16 v[120:123], v[88:91], v[168:171], v[120:123]
	v_mfma_f32_16x16x32_bf16 v[96:99], v[88:91], v[176:179], v[96:99]
	v_mfma_f32_16x16x32_bf16 v[92:95], v[112:115], v[176:179], v[92:95]
	v_mfma_f32_16x16x32_bf16 v[72:75], v[112:115], v[202:205], v[72:75]
	v_mfma_f32_16x16x32_bf16 v[76:79], v[88:91], v[202:205], v[76:79]
	v_mfma_f32_16x16x32_bf16 v[144:147], v[100:103], v[164:167], v[144:147]
	v_mfma_f32_16x16x32_bf16 v[140:143], v[124:127], v[164:167], v[140:143]
	v_mfma_f32_16x16x32_bf16 v[116:119], v[124:127], v[172:175], v[116:119]
	v_mfma_f32_16x16x32_bf16 v[120:123], v[100:103], v[172:175], v[120:123]
	v_mfma_f32_16x16x32_bf16 v[96:99], v[100:103], v[180:183], v[96:99]
	v_mfma_f32_16x16x32_bf16 v[92:95], v[124:127], v[180:183], v[92:95]
	v_mfma_f32_16x16x32_bf16 v[72:75], v[124:127], v[228:231], v[72:75]
	v_mfma_f32_16x16x32_bf16 v[76:79], v[100:103], v[228:231], v[76:79]
	s_setprio 0
	s_setprio 1
	v_mfma_f32_16x16x32_bf16 v[132:135], v[136:139], v[160:163], v[132:135]
	v_mfma_f32_16x16x32_bf16 v[128:131], v[152:155], v[160:163], v[128:131]
	v_mfma_f32_16x16x32_bf16 v[104:107], v[152:155], v[168:171], v[104:107]
	v_mfma_f32_16x16x32_bf16 v[108:111], v[136:139], v[168:171], v[108:111]
	v_mfma_f32_16x16x32_bf16 v[84:87], v[136:139], v[176:179], v[84:87]
	v_mfma_f32_16x16x32_bf16 v[80:83], v[152:155], v[176:179], v[80:83]
	v_mfma_f32_16x16x32_bf16 v[64:67], v[152:155], v[202:205], v[64:67]
	v_mfma_f32_16x16x32_bf16 v[68:71], v[136:139], v[202:205], v[68:71]
	v_mfma_f32_16x16x32_bf16 v[132:135], v[148:151], v[164:167], v[132:135]
	v_mfma_f32_16x16x32_bf16 v[128:131], v[156:159], v[164:167], v[128:131]
	v_mfma_f32_16x16x32_bf16 v[104:107], v[156:159], v[172:175], v[104:107]
	v_mfma_f32_16x16x32_bf16 v[108:111], v[148:151], v[172:175], v[108:111]
	v_mfma_f32_16x16x32_bf16 v[84:87], v[148:151], v[180:183], v[84:87]
	v_mfma_f32_16x16x32_bf16 v[80:83], v[156:159], v[180:183], v[80:83]
	v_mfma_f32_16x16x32_bf16 v[64:67], v[156:159], v[228:231], v[64:67]
	v_mfma_f32_16x16x32_bf16 v[68:71], v[148:151], v[228:231], v[68:71]
	s_setprio 0
	s_barrier
	s_add_i32 s46, s58, s2
	v_lshl_add_u64 v[208:209], v[208:209], 0, s[24:25]
	s_mov_b32 m0, s46
	ds_read_b128 v[160:163], v238 offset:49152
	ds_read_b128 v[164:167], v238 offset:50176
	ds_read_b128 v[168:171], v238 offset:51200
	ds_read_b128 v[172:175], v238 offset:52224
	ds_read_b128 v[176:179], v238 offset:53248
	ds_read_b128 v[180:183], v238 offset:54272
	ds_read_b128 v[202:205], v238 offset:55296
	ds_read_b128 v[228:231], v238 offset:56320
	global_load_lds_dwordx4 v[208:209], off
	s_add_i32 m0, s46, 0x2000
	s_add_u32 s44, s44, 0x40080
	v_lshl_add_u64 v[208:209], v[212:213], 0, s[24:25]
	s_addc_u32 s45, s45, 0
	s_add_i32 s46, s59, s2
	global_load_lds_dwordx4 v[208:209], off
	v_lshl_add_u64 v[208:209], s[44:45], 0, v[186:187]
	s_mov_b32 m0, s46
	s_nop 0
	global_load_lds_dwordx4 v[208:209], off
	v_lshl_add_u64 v[208:209], s[44:45], 0, v[190:191]
	s_add_i32 m0, s46, 0x2000
	s_nop 0
	global_load_lds_dwordx4 v[208:209], off
	v_lshl_add_u64 v[208:209], v[216:217], 0, s[24:25]
	s_mov_b32 m0, s49
	s_nop 0
	global_load_lds_dwordx4 v[208:209], off
	v_lshl_add_u64 v[208:209], v[220:221], 0, s[24:25]
	s_mov_b32 m0, s50
	s_nop 0
	global_load_lds_dwordx4 v[208:209], off
	s_waitcnt vmcnt(8)
	s_waitcnt lgkmcnt(0)
	s_barrier
	s_setprio 1
	s_waitcnt lgkmcnt(0)
	v_mfma_f32_16x16x32_bf16 v[60:63], v[88:91], v[160:163], v[60:63]
	v_mfma_f32_16x16x32_bf16 v[56:59], v[112:115], v[160:163], v[56:59]
	v_mfma_f32_16x16x32_bf16 v[40:43], v[112:115], v[168:171], v[40:43]
	v_mfma_f32_16x16x32_bf16 v[44:47], v[88:91], v[168:171], v[44:47]
	v_mfma_f32_16x16x32_bf16 v[28:31], v[88:91], v[176:179], v[28:31]
	v_mfma_f32_16x16x32_bf16 v[24:27], v[112:115], v[176:179], v[24:27]
	v_mfma_f32_16x16x32_bf16 v[8:11], v[112:115], v[202:205], v[8:11]
	v_mfma_f32_16x16x32_bf16 v[12:15], v[88:91], v[202:205], v[12:15]
	v_mfma_f32_16x16x32_bf16 v[60:63], v[100:103], v[164:167], v[60:63]
	v_mfma_f32_16x16x32_bf16 v[56:59], v[124:127], v[164:167], v[56:59]
	v_mfma_f32_16x16x32_bf16 v[40:43], v[124:127], v[172:175], v[40:43]
	v_mfma_f32_16x16x32_bf16 v[44:47], v[100:103], v[172:175], v[44:47]
	v_mfma_f32_16x16x32_bf16 v[28:31], v[100:103], v[180:183], v[28:31]
	v_mfma_f32_16x16x32_bf16 v[24:27], v[124:127], v[180:183], v[24:27]
	v_mfma_f32_16x16x32_bf16 v[8:11], v[124:127], v[228:231], v[8:11]
	v_mfma_f32_16x16x32_bf16 v[12:15], v[100:103], v[228:231], v[12:15]
	s_setprio 0
	s_setprio 1
	v_mfma_f32_16x16x32_bf16 v[52:55], v[136:139], v[160:163], v[52:55]
	v_mfma_f32_16x16x32_bf16 v[48:51], v[152:155], v[160:163], v[48:51]
	v_mfma_f32_16x16x32_bf16 v[32:35], v[152:155], v[168:171], v[32:35]
	v_mfma_f32_16x16x32_bf16 v[36:39], v[136:139], v[168:171], v[36:39]
	v_mfma_f32_16x16x32_bf16 v[20:23], v[136:139], v[176:179], v[20:23]
	v_mfma_f32_16x16x32_bf16 v[16:19], v[152:155], v[176:179], v[16:19]
	v_mfma_f32_16x16x32_bf16 v[0:3], v[152:155], v[202:205], v[0:3]
	v_mfma_f32_16x16x32_bf16 v[4:7], v[136:139], v[202:205], v[4:7]
	v_mfma_f32_16x16x32_bf16 v[52:55], v[148:151], v[164:167], v[52:55]
	v_mfma_f32_16x16x32_bf16 v[48:51], v[156:159], v[164:167], v[48:51]
	v_mfma_f32_16x16x32_bf16 v[32:35], v[156:159], v[172:175], v[32:35]
	v_mfma_f32_16x16x32_bf16 v[36:39], v[148:151], v[172:175], v[36:39]
	v_mfma_f32_16x16x32_bf16 v[20:23], v[148:151], v[180:183], v[20:23]
	v_mfma_f32_16x16x32_bf16 v[16:19], v[156:159], v[180:183], v[16:19]
	v_mfma_f32_16x16x32_bf16 v[0:3], v[156:159], v[228:231], v[0:3]
	v_mfma_f32_16x16x32_bf16 v[4:7], v[148:151], v[228:231], v[4:7]
	s_setprio 0
	s_barrier
	s_add_i32 s57, s57, 2
	s_add_u32 s42, s42, 0x100
	s_addc_u32 s43, s43, 0
	s_add_u32 s55, s55, 0x100
	s_addc_u32 s56, s56, 0
	s_cmp_gt_u32 s57, 13
	s_cbranch_scc0 .LBB0_646
	s_and_b64 vcc, exec, s[26:27]
	s_cbranch_vccz .LBB0_649
	s_barrier

.LBB0_751:
	ds_read_b128 v[156:159], v152
	ds_read_b128 v[160:163], v152 offset:1024
	ds_read_b128 v[164:167], v152 offset:2048
	ds_read_b128 v[168:171], v152 offset:3072
	ds_read_b128 v[172:175], v153
	ds_read_b128 v[176:179], v153 offset:1024
	ds_read_b128 v[180:183], v153 offset:2048
	ds_read_b128 v[184:187], v153 offset:3072
	s_add_u32 s38, s36, 0xfffc0080
	s_addc_u32 s39, s37, -1
	s_cmp_eq_u32 s54, 12
	s_cselect_b32 s41, s25, s39
	s_cselect_b32 s40, s50, s38
	s_cselect_b32 s39, s23, s53
	s_cselect_b32 s38, s51, s52
	v_lshl_add_u64 v[146:147], s[36:37], 0, v[138:139]
	s_add_i32 m0, s31, 0xc000
	ds_read_b128 v[188:191], v154
	ds_read_b128 v[192:195], v154 offset:1024
	ds_read_b128 v[196:199], v154 offset:2048
	ds_read_b128 v[200:203], v154 offset:3072
	ds_read_b128 v[204:207], v154 offset:4096
	ds_read_b128 v[208:211], v154 offset:5120
	ds_read_b128 v[216:219], v154 offset:6144
	ds_read_b128 v[220:223], v154 offset:7168
	global_load_lds_dwordx4 v[146:147], off
	v_lshl_add_u64 v[146:147], s[36:37], 0, v[140:141]
	s_add_i32 m0, s31, 0xe000
	s_nop 0
	global_load_lds_dwordx4 v[146:147], off
	s_waitcnt vmcnt(8)
	s_waitcnt lgkmcnt(0)
	s_barrier
	s_setprio 1
	s_waitcnt lgkmcnt(0)
	v_mfma_f32_16x16x32_bf16 v[124:127], v[156:159], v[188:191], v[124:127]
	v_mfma_f32_16x16x32_bf16 v[120:123], v[164:167], v[188:191], v[120:123]
	v_mfma_f32_16x16x32_bf16 v[104:107], v[164:167], v[196:199], v[104:107]
	v_mfma_f32_16x16x32_bf16 v[108:111], v[156:159], v[196:199], v[108:111]
	v_mfma_f32_16x16x32_bf16 v[92:95], v[156:159], v[204:207], v[92:95]
	v_mfma_f32_16x16x32_bf16 v[88:91], v[164:167], v[204:207], v[88:91]
	v_mfma_f32_16x16x32_bf16 v[72:75], v[164:167], v[216:219], v[72:75]
	v_mfma_f32_16x16x32_bf16 v[76:79], v[156:159], v[216:219], v[76:79]
	v_mfma_f32_16x16x32_bf16 v[124:127], v[160:163], v[192:195], v[124:127]
	v_mfma_f32_16x16x32_bf16 v[120:123], v[168:171], v[192:195], v[120:123]
	v_mfma_f32_16x16x32_bf16 v[104:107], v[168:171], v[200:203], v[104:107]
	v_mfma_f32_16x16x32_bf16 v[108:111], v[160:163], v[200:203], v[108:111]
	v_mfma_f32_16x16x32_bf16 v[92:95], v[160:163], v[208:211], v[92:95]
	v_mfma_f32_16x16x32_bf16 v[88:91], v[168:171], v[208:211], v[88:91]
	v_mfma_f32_16x16x32_bf16 v[72:75], v[168:171], v[220:223], v[72:75]
	v_mfma_f32_16x16x32_bf16 v[76:79], v[160:163], v[220:223], v[76:79]
	s_setprio 0
	s_setprio 1
	v_mfma_f32_16x16x32_bf16 v[116:119], v[172:175], v[188:191], v[116:119]
	v_mfma_f32_16x16x32_bf16 v[112:115], v[180:183], v[188:191], v[112:115]
	v_mfma_f32_16x16x32_bf16 v[96:99], v[180:183], v[196:199], v[96:99]
	v_mfma_f32_16x16x32_bf16 v[100:103], v[172:175], v[196:199], v[100:103]
	v_mfma_f32_16x16x32_bf16 v[84:87], v[172:175], v[204:207], v[84:87]
	v_mfma_f32_16x16x32_bf16 v[80:83], v[180:183], v[204:207], v[80:83]
	v_mfma_f32_16x16x32_bf16 v[64:67], v[180:183], v[216:219], v[64:67]
	v_mfma_f32_16x16x32_bf16 v[68:71], v[172:175], v[216:219], v[68:71]
	v_mfma_f32_16x16x32_bf16 v[116:119], v[176:179], v[192:195], v[116:119]
	v_mfma_f32_16x16x32_bf16 v[112:115], v[184:187], v[192:195], v[112:115]
	v_mfma_f32_16x16x32_bf16 v[96:99], v[184:187], v[200:203], v[96:99]
	v_mfma_f32_16x16x32_bf16 v[100:103], v[176:179], v[200:203], v[100:103]
	v_mfma_f32_16x16x32_bf16 v[84:87], v[176:179], v[208:211], v[84:87]
	v_mfma_f32_16x16x32_bf16 v[80:83], v[184:187], v[208:211], v[80:83]
	v_mfma_f32_16x16x32_bf16 v[64:67], v[184:187], v[220:223], v[64:67]
	v_mfma_f32_16x16x32_bf16 v[68:71], v[176:179], v[220:223], v[68:71]
	s_setprio 0
	s_barrier
	s_add_i32 s55, s47, s33
	v_lshl_add_u64 v[146:147], s[38:39], 0, v[132:133]
	s_mov_b32 m0, s55
	ds_read_b128 v[188:191], v154 offset:16384
	ds_read_b128 v[192:195], v154 offset:17408
	ds_read_b128 v[196:199], v154 offset:18432
	ds_read_b128 v[200:203], v154 offset:19456
	ds_read_b128 v[204:207], v154 offset:20480
	ds_read_b128 v[208:211], v154 offset:21504
	ds_read_b128 v[216:219], v154 offset:22528
	ds_read_b128 v[220:223], v154 offset:23552
	global_load_lds_dwordx4 v[146:147], off
	s_add_i32 m0, s55, 0x2000
	s_add_u32 s56, s38, 0x40000
	v_lshl_add_u64 v[212:213], s[38:39], 0, v[128:129]
	s_addc_u32 s57, s39, 0
	s_add_i32 s55, s48, s33
	global_load_lds_dwordx4 v[212:213], off
	v_lshl_add_u64 v[224:225], s[56:57], 0, v[132:133]
	s_mov_b32 m0, s55
	v_lshl_add_u64 v[226:227], s[40:41], 0, v[130:131]
	global_load_lds_dwordx4 v[224:225], off
	v_lshl_add_u64 v[224:225], s[56:57], 0, v[128:129]
	s_add_i32 m0, s55, 0x2000
	s_nop 0
	global_load_lds_dwordx4 v[224:225], off
	v_lshl_add_u64 v[224:225], s[40:41], 0, v[134:135]
	s_mov_b32 m0, s31
	s_nop 0
	global_load_lds_dwordx4 v[224:225], off
	s_mov_b32 m0, s34
	s_nop 0
	global_load_lds_dwordx4 v[226:227], off
	s_waitcnt vmcnt(8)
	s_waitcnt lgkmcnt(0)
	s_barrier
	s_setprio 1
	s_waitcnt lgkmcnt(0)
	v_mfma_f32_16x16x32_bf16 v[60:63], v[156:159], v[188:191], v[60:63]
	v_mfma_f32_16x16x32_bf16 v[56:59], v[164:167], v[188:191], v[56:59]
	v_mfma_f32_16x16x32_bf16 v[40:43], v[164:167], v[196:199], v[40:43]
	v_mfma_f32_16x16x32_bf16 v[44:47], v[156:159], v[196:199], v[44:47]
	v_mfma_f32_16x16x32_bf16 v[28:31], v[156:159], v[204:207], v[28:31]
	v_mfma_f32_16x16x32_bf16 v[24:27], v[164:167], v[204:207], v[24:27]
	v_mfma_f32_16x16x32_bf16 v[8:11], v[164:167], v[216:219], v[8:11]
	v_mfma_f32_16x16x32_bf16 v[12:15], v[156:159], v[216:219], v[12:15]
	v_mfma_f32_16x16x32_bf16 v[60:63], v[160:163], v[192:195], v[60:63]
	v_mfma_f32_16x16x32_bf16 v[56:59], v[168:171], v[192:195], v[56:59]
	v_mfma_f32_16x16x32_bf16 v[40:43], v[168:171], v[200:203], v[40:43]
	v_mfma_f32_16x16x32_bf16 v[44:47], v[160:163], v[200:203], v[44:47]
	v_mfma_f32_16x16x32_bf16 v[28:31], v[160:163], v[208:211], v[28:31]
	v_mfma_f32_16x16x32_bf16 v[24:27], v[168:171], v[208:211], v[24:27]
	v_mfma_f32_16x16x32_bf16 v[8:11], v[168:171], v[220:223], v[8:11]
	v_mfma_f32_16x16x32_bf16 v[12:15], v[160:163], v[220:223], v[12:15]
	s_setprio 0
	s_setprio 1
	v_mfma_f32_16x16x32_bf16 v[52:55], v[172:175], v[188:191], v[52:55]
	v_mfma_f32_16x16x32_bf16 v[48:51], v[180:183], v[188:191], v[48:51]
	v_mfma_f32_16x16x32_bf16 v[32:35], v[180:183], v[196:199], v[32:35]
	v_mfma_f32_16x16x32_bf16 v[36:39], v[172:175], v[196:199], v[36:39]
	v_mfma_f32_16x16x32_bf16 v[20:23], v[172:175], v[204:207], v[20:23]
	v_mfma_f32_16x16x32_bf16 v[16:19], v[180:183], v[204:207], v[16:19]
	v_mfma_f32_16x16x32_bf16 v[0:3], v[180:183], v[216:219], v[0:3]
	v_mfma_f32_16x16x32_bf16 v[4:7], v[172:175], v[216:219], v[4:7]
	v_mfma_f32_16x16x32_bf16 v[52:55], v[176:179], v[192:195], v[52:55]
	v_mfma_f32_16x16x32_bf16 v[48:51], v[184:187], v[192:195], v[48:51]
	v_mfma_f32_16x16x32_bf16 v[32:35], v[184:187], v[200:203], v[32:35]
	v_mfma_f32_16x16x32_bf16 v[36:39], v[176:179], v[200:203], v[36:39]
	v_mfma_f32_16x16x32_bf16 v[20:23], v[176:179], v[208:211], v[20:23]
	v_mfma_f32_16x16x32_bf16 v[16:19], v[184:187], v[208:211], v[16:19]
	v_mfma_f32_16x16x32_bf16 v[0:3], v[184:187], v[220:223], v[0:3]
	v_mfma_f32_16x16x32_bf16 v[4:7], v[176:179], v[220:223], v[4:7]
	s_setprio 0
	s_barrier
	s_add_i32 s55, 0, 0x18000
	v_add_u32_e32 v155, s55, v148
	s_add_i32 s56, 0, 0x1c000
	ds_read_b128 v[156:159], v155
	ds_read_b128 v[160:163], v155 offset:1024
	ds_read_b128 v[164:167], v155 offset:2048
	ds_read_b128 v[168:171], v155 offset:3072
	v_add_u32_e32 v155, s56, v148
	ds_read_b128 v[172:175], v155
	ds_read_b128 v[176:179], v155 offset:1024
	ds_read_b128 v[180:183], v155 offset:2048
	ds_read_b128 v[184:187], v155 offset:3072
	s_add_u32 s40, s40, 0x40000
	s_addc_u32 s41, s41, 0
	s_mov_b32 m0, s35
	v_lshl_add_u64 v[228:229], s[40:41], 0, v[134:135]
	ds_read_b128 v[188:191], v154 offset:32768
	ds_read_b128 v[192:195], v154 offset:33792
	ds_read_b128 v[196:199], v154 offset:34816
	ds_read_b128 v[200:203], v154 offset:35840
	ds_read_b128 v[204:207], v154 offset:36864
	ds_read_b128 v[208:211], v154 offset:37888
	ds_read_b128 v[216:219], v154 offset:38912
	ds_read_b128 v[220:223], v154 offset:39936
	global_load_lds_dwordx4 v[228:229], off
	v_lshl_add_u64 v[228:229], s[40:41], 0, v[130:131]
	s_mov_b32 m0, s42
	s_nop 0
	global_load_lds_dwordx4 v[228:229], off
	s_waitcnt vmcnt(8)
	s_waitcnt lgkmcnt(0)
	s_barrier
	s_setprio 1
	s_waitcnt lgkmcnt(0)
	v_mfma_f32_16x16x32_bf16 v[124:127], v[156:159], v[188:191], v[124:127]
	v_mfma_f32_16x16x32_bf16 v[120:123], v[164:167], v[188:191], v[120:123]
	v_mfma_f32_16x16x32_bf16 v[104:107], v[164:167], v[196:199], v[104:107]
	v_mfma_f32_16x16x32_bf16 v[108:111], v[156:159], v[196:199], v[108:111]
	v_mfma_f32_16x16x32_bf16 v[92:95], v[156:159], v[204:207], v[92:95]
	v_mfma_f32_16x16x32_bf16 v[88:91], v[164:167], v[204:207], v[88:91]
	v_mfma_f32_16x16x32_bf16 v[72:75], v[164:167], v[216:219], v[72:75]
	v_mfma_f32_16x16x32_bf16 v[76:79], v[156:159], v[216:219], v[76:79]
	v_mfma_f32_16x16x32_bf16 v[124:127], v[160:163], v[192:195], v[124:127]
	v_mfma_f32_16x16x32_bf16 v[120:123], v[168:171], v[192:195], v[120:123]
	v_mfma_f32_16x16x32_bf16 v[104:107], v[168:171], v[200:203], v[104:107]
	v_mfma_f32_16x16x32_bf16 v[108:111], v[160:163], v[200:203], v[108:111]
	v_mfma_f32_16x16x32_bf16 v[92:95], v[160:163], v[208:211], v[92:95]
	v_mfma_f32_16x16x32_bf16 v[88:91], v[168:171], v[208:211], v[88:91]
	v_mfma_f32_16x16x32_bf16 v[72:75], v[168:171], v[220:223], v[72:75]
	v_mfma_f32_16x16x32_bf16 v[76:79], v[160:163], v[220:223], v[76:79]
	s_setprio 0
	s_setprio 1
	v_mfma_f32_16x16x32_bf16 v[116:119], v[172:175], v[188:191], v[116:119]
	v_mfma_f32_16x16x32_bf16 v[112:115], v[180:183], v[188:191], v[112:115]
	v_mfma_f32_16x16x32_bf16 v[96:99], v[180:183], v[196:199], v[96:99]
	v_mfma_f32_16x16x32_bf16 v[100:103], v[172:175], v[196:199], v[100:103]
	v_mfma_f32_16x16x32_bf16 v[84:87], v[172:175], v[204:207], v[84:87]
	v_mfma_f32_16x16x32_bf16 v[80:83], v[180:183], v[204:207], v[80:83]
	v_mfma_f32_16x16x32_bf16 v[64:67], v[180:183], v[216:219], v[64:67]
	v_mfma_f32_16x16x32_bf16 v[68:71], v[172:175], v[216:219], v[68:71]
	v_mfma_f32_16x16x32_bf16 v[116:119], v[176:179], v[192:195], v[116:119]
	v_mfma_f32_16x16x32_bf16 v[112:115], v[184:187], v[192:195], v[112:115]
	v_mfma_f32_16x16x32_bf16 v[96:99], v[184:187], v[200:203], v[96:99]
	v_mfma_f32_16x16x32_bf16 v[100:103], v[176:179], v[200:203], v[100:103]
	v_mfma_f32_16x16x32_bf16 v[84:87], v[176:179], v[208:211], v[84:87]
	v_mfma_f32_16x16x32_bf16 v[80:83], v[184:187], v[208:211], v[80:83]
	v_mfma_f32_16x16x32_bf16 v[64:67], v[184:187], v[220:223], v[64:67]
	v_mfma_f32_16x16x32_bf16 v[68:71], v[176:179], v[220:223], v[68:71]
	s_setprio 0
	s_barrier
	s_add_i32 s40, s55, s33
	v_lshl_add_u64 v[146:147], v[146:147], 0, s[18:19]
	s_mov_b32 m0, s40
	ds_read_b128 v[188:191], v154 offset:49152
	ds_read_b128 v[192:195], v154 offset:50176
	ds_read_b128 v[196:199], v154 offset:51200
	ds_read_b128 v[200:203], v154 offset:52224
	ds_read_b128 v[204:207], v154 offset:53248
	ds_read_b128 v[208:211], v154 offset:54272
	ds_read_b128 v[216:219], v154 offset:55296
	ds_read_b128 v[220:223], v154 offset:56320
	global_load_lds_dwordx4 v[146:147], off
	s_add_i32 m0, s40, 0x2000
	s_add_u32 s38, s38, 0x40080
	v_lshl_add_u64 v[146:147], v[212:213], 0, s[18:19]
	s_addc_u32 s39, s39, 0
	s_add_i32 s40, s56, s33
	global_load_lds_dwordx4 v[146:147], off
	v_lshl_add_u64 v[146:147], s[38:39], 0, v[132:133]
	s_mov_b32 m0, s40
	s_nop 0
	global_load_lds_dwordx4 v[146:147], off
	v_lshl_add_u64 v[146:147], s[38:39], 0, v[128:129]
	s_add_i32 m0, s40, 0x2000
	s_nop 0
	global_load_lds_dwordx4 v[146:147], off
	v_lshl_add_u64 v[146:147], v[224:225], 0, s[18:19]
	s_mov_b32 m0, s44
	s_nop 0
	global_load_lds_dwordx4 v[146:147], off
	v_lshl_add_u64 v[146:147], v[226:227], 0, s[18:19]
	s_mov_b32 m0, s45
	s_nop 0
	global_load_lds_dwordx4 v[146:147], off
	s_waitcnt vmcnt(8)
	s_waitcnt lgkmcnt(0)
	s_barrier
	s_setprio 1
	s_waitcnt lgkmcnt(0)
	v_mfma_f32_16x16x32_bf16 v[60:63], v[156:159], v[188:191], v[60:63]
	v_mfma_f32_16x16x32_bf16 v[56:59], v[164:167], v[188:191], v[56:59]
	v_mfma_f32_16x16x32_bf16 v[40:43], v[164:167], v[196:199], v[40:43]
	v_mfma_f32_16x16x32_bf16 v[44:47], v[156:159], v[196:199], v[44:47]
	v_mfma_f32_16x16x32_bf16 v[28:31], v[156:159], v[204:207], v[28:31]
	v_mfma_f32_16x16x32_bf16 v[24:27], v[164:167], v[204:207], v[24:27]
	v_mfma_f32_16x16x32_bf16 v[8:11], v[164:167], v[216:219], v[8:11]
	v_mfma_f32_16x16x32_bf16 v[12:15], v[156:159], v[216:219], v[12:15]
	v_mfma_f32_16x16x32_bf16 v[60:63], v[160:163], v[192:195], v[60:63]
	v_mfma_f32_16x16x32_bf16 v[56:59], v[168:171], v[192:195], v[56:59]
	v_mfma_f32_16x16x32_bf16 v[40:43], v[168:171], v[200:203], v[40:43]
	v_mfma_f32_16x16x32_bf16 v[44:47], v[160:163], v[200:203], v[44:47]
	v_mfma_f32_16x16x32_bf16 v[28:31], v[160:163], v[208:211], v[28:31]
	v_mfma_f32_16x16x32_bf16 v[24:27], v[168:171], v[208:211], v[24:27]
	v_mfma_f32_16x16x32_bf16 v[8:11], v[168:171], v[220:223], v[8:11]
	v_mfma_f32_16x16x32_bf16 v[12:15], v[160:163], v[220:223], v[12:15]
	s_setprio 0
	s_setprio 1
	v_mfma_f32_16x16x32_bf16 v[52:55], v[172:175], v[188:191], v[52:55]
	v_mfma_f32_16x16x32_bf16 v[48:51], v[180:183], v[188:191], v[48:51]
	v_mfma_f32_16x16x32_bf16 v[32:35], v[180:183], v[196:199], v[32:35]
	v_mfma_f32_16x16x32_bf16 v[36:39], v[172:175], v[196:199], v[36:39]
	v_mfma_f32_16x16x32_bf16 v[20:23], v[172:175], v[204:207], v[20:23]
	v_mfma_f32_16x16x32_bf16 v[16:19], v[180:183], v[204:207], v[16:19]
	v_mfma_f32_16x16x32_bf16 v[0:3], v[180:183], v[216:219], v[0:3]
	v_mfma_f32_16x16x32_bf16 v[4:7], v[172:175], v[216:219], v[4:7]
	v_mfma_f32_16x16x32_bf16 v[52:55], v[176:179], v[192:195], v[52:55]
	v_mfma_f32_16x16x32_bf16 v[48:51], v[184:187], v[192:195], v[48:51]
	v_mfma_f32_16x16x32_bf16 v[32:35], v[184:187], v[200:203], v[32:35]
	v_mfma_f32_16x16x32_bf16 v[36:39], v[176:179], v[200:203], v[36:39]
	v_mfma_f32_16x16x32_bf16 v[20:23], v[176:179], v[208:211], v[20:23]
	v_mfma_f32_16x16x32_bf16 v[16:19], v[184:187], v[208:211], v[16:19]
	v_mfma_f32_16x16x32_bf16 v[0:3], v[184:187], v[220:223], v[0:3]
	v_mfma_f32_16x16x32_bf16 v[4:7], v[176:179], v[220:223], v[4:7]
	s_setprio 0
	s_barrier
	s_add_i32 s54, s54, 2
	s_add_u32 s36, s36, 0x100
	s_addc_u32 s37, s37, 0
	s_add_u32 s52, s52, 0x100
	s_addc_u32 s53, s53, 0
	s_cmp_gt_u32 s54, 13
	s_cbranch_scc0 .LBB0_751
	s_and_b64 vcc, exec, s[20:21]
	s_cbranch_vccz .LBB0_754
	s_barrier

.LBB0_828:
	ds_read_b128 v[142:145], v195
	ds_read_b128 v[146:149], v195 offset:1024
	ds_read_b128 v[150:153], v195 offset:2048
	ds_read_b128 v[154:157], v195 offset:3072
	ds_read_b128 v[158:161], v196
	ds_read_b128 v[162:165], v196 offset:1024
	ds_read_b128 v[166:169], v196 offset:2048
	ds_read_b128 v[170:173], v196 offset:3072
	s_add_u32 s40, s38, 0xfff00080
	s_addc_u32 s41, s39, -1
	s_cmp_eq_u32 s58, 60
	s_cselect_b32 s43, s27, s41
	s_cselect_b32 s42, s54, s40
	s_cselect_b32 s41, s25, s57
	s_cselect_b32 s40, s55, s56
	v_lshl_add_u64 v[190:191], s[38:39], 0, v[134:135]
	s_add_i32 m0, s2, 0xc000
	ds_read_b128 v[174:177], v197
	ds_read_b128 v[178:181], v197 offset:1024
	ds_read_b128 v[182:185], v197 offset:2048
	ds_read_b128 v[186:189], v197 offset:3072
	ds_read_b128 v[198:201], v197 offset:4096
	ds_read_b128 v[202:205], v197 offset:5120
	ds_read_b128 v[206:209], v197 offset:6144
	ds_read_b128 v[210:213], v197 offset:7168
	global_load_lds_dwordx4 v[190:191], off
	v_lshl_add_u64 v[190:191], s[38:39], 0, v[136:137]
	s_add_i32 m0, s2, 0xe000
	s_nop 0
	global_load_lds_dwordx4 v[190:191], off
	s_waitcnt vmcnt(8)
	s_waitcnt lgkmcnt(0)
	s_barrier
	s_setprio 1
	s_waitcnt lgkmcnt(0)
	v_mfma_f32_16x16x32_bf16 v[124:127], v[142:145], v[174:177], v[124:127]
	v_mfma_f32_16x16x32_bf16 v[120:123], v[150:153], v[174:177], v[120:123]
	v_mfma_f32_16x16x32_bf16 v[104:107], v[150:153], v[182:185], v[104:107]
	v_mfma_f32_16x16x32_bf16 v[108:111], v[142:145], v[182:185], v[108:111]
	v_mfma_f32_16x16x32_bf16 v[92:95], v[142:145], v[198:201], v[92:95]
	v_mfma_f32_16x16x32_bf16 v[88:91], v[150:153], v[198:201], v[88:91]
	v_mfma_f32_16x16x32_bf16 v[72:75], v[150:153], v[206:209], v[72:75]
	v_mfma_f32_16x16x32_bf16 v[76:79], v[142:145], v[206:209], v[76:79]
	v_mfma_f32_16x16x32_bf16 v[124:127], v[146:149], v[178:181], v[124:127]
	v_mfma_f32_16x16x32_bf16 v[120:123], v[154:157], v[178:181], v[120:123]
	v_mfma_f32_16x16x32_bf16 v[104:107], v[154:157], v[186:189], v[104:107]
	v_mfma_f32_16x16x32_bf16 v[108:111], v[146:149], v[186:189], v[108:111]
	v_mfma_f32_16x16x32_bf16 v[92:95], v[146:149], v[202:205], v[92:95]
	v_mfma_f32_16x16x32_bf16 v[88:91], v[154:157], v[202:205], v[88:91]
	v_mfma_f32_16x16x32_bf16 v[72:75], v[154:157], v[210:213], v[72:75]
	v_mfma_f32_16x16x32_bf16 v[76:79], v[146:149], v[210:213], v[76:79]
	s_setprio 0
	s_setprio 1
	v_mfma_f32_16x16x32_bf16 v[116:119], v[158:161], v[174:177], v[116:119]
	v_mfma_f32_16x16x32_bf16 v[112:115], v[166:169], v[174:177], v[112:115]
	v_mfma_f32_16x16x32_bf16 v[96:99], v[166:169], v[182:185], v[96:99]
	v_mfma_f32_16x16x32_bf16 v[100:103], v[158:161], v[182:185], v[100:103]
	v_mfma_f32_16x16x32_bf16 v[84:87], v[158:161], v[198:201], v[84:87]
	v_mfma_f32_16x16x32_bf16 v[80:83], v[166:169], v[198:201], v[80:83]
	v_mfma_f32_16x16x32_bf16 v[64:67], v[166:169], v[206:209], v[64:67]
	v_mfma_f32_16x16x32_bf16 v[68:71], v[158:161], v[206:209], v[68:71]
	v_mfma_f32_16x16x32_bf16 v[116:119], v[162:165], v[178:181], v[116:119]
	v_mfma_f32_16x16x32_bf16 v[112:115], v[170:173], v[178:181], v[112:115]
	v_mfma_f32_16x16x32_bf16 v[96:99], v[170:173], v[186:189], v[96:99]
	v_mfma_f32_16x16x32_bf16 v[100:103], v[162:165], v[186:189], v[100:103]
	v_mfma_f32_16x16x32_bf16 v[84:87], v[162:165], v[202:205], v[84:87]
	v_mfma_f32_16x16x32_bf16 v[80:83], v[170:173], v[202:205], v[80:83]
	v_mfma_f32_16x16x32_bf16 v[64:67], v[170:173], v[210:213], v[64:67]
	v_mfma_f32_16x16x32_bf16 v[68:71], v[162:165], v[210:213], v[68:71]
	s_setprio 0
	s_barrier
	s_add_i32 s59, s46, s3
	v_lshl_add_u64 v[190:191], s[40:41], 0, v[128:129]
	s_mov_b32 m0, s59
	ds_read_b128 v[174:177], v197 offset:16384
	ds_read_b128 v[178:181], v197 offset:17408
	ds_read_b128 v[182:185], v197 offset:18432
	ds_read_b128 v[186:189], v197 offset:19456
	ds_read_b128 v[198:201], v197 offset:20480
	ds_read_b128 v[202:205], v197 offset:21504
	ds_read_b128 v[206:209], v197 offset:22528
	ds_read_b128 v[210:213], v197 offset:23552
	global_load_lds_dwordx4 v[190:191], off
	s_add_i32 m0, s59, 0x2000
	s_add_u32 s62, s40, 0x100000
	v_lshl_add_u64 v[214:215], s[40:41], 0, v[130:131]
	s_addc_u32 s63, s41, 0
	s_add_i32 s59, s47, s3
	global_load_lds_dwordx4 v[214:215], off
	v_lshl_add_u64 v[216:217], s[62:63], 0, v[128:129]
	s_mov_b32 m0, s59
	v_lshl_add_u64 v[218:219], s[42:43], 0, v[130:131]
	global_load_lds_dwordx4 v[216:217], off
	v_lshl_add_u64 v[216:217], s[62:63], 0, v[130:131]
	s_add_i32 m0, s59, 0x2000
	s_nop 0
	global_load_lds_dwordx4 v[216:217], off
	v_lshl_add_u64 v[216:217], s[42:43], 0, v[128:129]
	s_mov_b32 m0, s2
	s_nop 0
	global_load_lds_dwordx4 v[216:217], off
	s_mov_b32 m0, s33
	s_nop 0
	global_load_lds_dwordx4 v[218:219], off
	s_waitcnt vmcnt(8)
	s_waitcnt lgkmcnt(0)
	s_barrier
	s_setprio 1
	s_waitcnt lgkmcnt(0)
	v_mfma_f32_16x16x32_bf16 v[60:63], v[142:145], v[174:177], v[60:63]
	v_mfma_f32_16x16x32_bf16 v[56:59], v[150:153], v[174:177], v[56:59]
	v_mfma_f32_16x16x32_bf16 v[40:43], v[150:153], v[182:185], v[40:43]
	v_mfma_f32_16x16x32_bf16 v[44:47], v[142:145], v[182:185], v[44:47]
	v_mfma_f32_16x16x32_bf16 v[28:31], v[142:145], v[198:201], v[28:31]
	v_mfma_f32_16x16x32_bf16 v[24:27], v[150:153], v[198:201], v[24:27]
	v_mfma_f32_16x16x32_bf16 v[8:11], v[150:153], v[206:209], v[8:11]
	v_mfma_f32_16x16x32_bf16 v[12:15], v[142:145], v[206:209], v[12:15]
	v_mfma_f32_16x16x32_bf16 v[60:63], v[146:149], v[178:181], v[60:63]
	v_mfma_f32_16x16x32_bf16 v[56:59], v[154:157], v[178:181], v[56:59]
	v_mfma_f32_16x16x32_bf16 v[40:43], v[154:157], v[186:189], v[40:43]
	v_mfma_f32_16x16x32_bf16 v[44:47], v[146:149], v[186:189], v[44:47]
	v_mfma_f32_16x16x32_bf16 v[28:31], v[146:149], v[202:205], v[28:31]
	v_mfma_f32_16x16x32_bf16 v[24:27], v[154:157], v[202:205], v[24:27]
	v_mfma_f32_16x16x32_bf16 v[8:11], v[154:157], v[210:213], v[8:11]
	v_mfma_f32_16x16x32_bf16 v[12:15], v[146:149], v[210:213], v[12:15]
	s_setprio 0
	s_setprio 1
	v_mfma_f32_16x16x32_bf16 v[52:55], v[158:161], v[174:177], v[52:55]
	v_mfma_f32_16x16x32_bf16 v[48:51], v[166:169], v[174:177], v[48:51]
	v_mfma_f32_16x16x32_bf16 v[32:35], v[166:169], v[182:185], v[32:35]
	v_mfma_f32_16x16x32_bf16 v[36:39], v[158:161], v[182:185], v[36:39]
	v_mfma_f32_16x16x32_bf16 v[20:23], v[158:161], v[198:201], v[20:23]
	v_mfma_f32_16x16x32_bf16 v[16:19], v[166:169], v[198:201], v[16:19]
	v_mfma_f32_16x16x32_bf16 v[0:3], v[166:169], v[206:209], v[0:3]
	v_mfma_f32_16x16x32_bf16 v[4:7], v[158:161], v[206:209], v[4:7]
	v_mfma_f32_16x16x32_bf16 v[52:55], v[162:165], v[178:181], v[52:55]
	v_mfma_f32_16x16x32_bf16 v[48:51], v[170:173], v[178:181], v[48:51]
	v_mfma_f32_16x16x32_bf16 v[32:35], v[170:173], v[186:189], v[32:35]
	v_mfma_f32_16x16x32_bf16 v[36:39], v[162:165], v[186:189], v[36:39]
	v_mfma_f32_16x16x32_bf16 v[20:23], v[162:165], v[202:205], v[20:23]
	v_mfma_f32_16x16x32_bf16 v[16:19], v[170:173], v[202:205], v[16:19]
	v_mfma_f32_16x16x32_bf16 v[0:3], v[170:173], v[210:213], v[0:3]
	v_mfma_f32_16x16x32_bf16 v[4:7], v[162:165], v[210:213], v[4:7]
	s_setprio 0
	s_barrier
	s_add_i32 s59, 0, 0x18000
	s_add_i32 s62, 0, 0x1c000
	v_add_u32_e32 v154, s59, v192
	v_add_u32_e32 v170, s62, v192
	ds_read_b128 v[142:145], v154
	ds_read_b128 v[146:149], v154 offset:1024
	ds_read_b128 v[150:153], v154 offset:2048
	ds_read_b128 v[154:157], v154 offset:3072
	ds_read_b128 v[158:161], v170
	ds_read_b128 v[162:165], v170 offset:1024
	ds_read_b128 v[166:169], v170 offset:2048
	ds_read_b128 v[170:173], v170 offset:3072
	s_add_u32 s42, s42, 0x100000
	s_addc_u32 s43, s43, 0
	s_mov_b32 m0, s34
	v_lshl_add_u64 v[220:221], s[42:43], 0, v[128:129]
	ds_read_b128 v[174:177], v197 offset:32768
	ds_read_b128 v[178:181], v197 offset:33792
	ds_read_b128 v[182:185], v197 offset:34816
	ds_read_b128 v[186:189], v197 offset:35840
	ds_read_b128 v[198:201], v197 offset:36864
	ds_read_b128 v[202:205], v197 offset:37888
	ds_read_b128 v[206:209], v197 offset:38912
	ds_read_b128 v[210:213], v197 offset:39936
	global_load_lds_dwordx4 v[220:221], off
	v_lshl_add_u64 v[220:221], s[42:43], 0, v[130:131]
	s_mov_b32 m0, s35
	s_nop 0
	global_load_lds_dwordx4 v[220:221], off
	s_waitcnt vmcnt(8)
	s_waitcnt lgkmcnt(0)
	s_barrier
	s_setprio 1
	s_waitcnt lgkmcnt(0)
	v_mfma_f32_16x16x32_bf16 v[124:127], v[142:145], v[174:177], v[124:127]
	v_mfma_f32_16x16x32_bf16 v[120:123], v[150:153], v[174:177], v[120:123]
	v_mfma_f32_16x16x32_bf16 v[104:107], v[150:153], v[182:185], v[104:107]
	v_mfma_f32_16x16x32_bf16 v[108:111], v[142:145], v[182:185], v[108:111]
	v_mfma_f32_16x16x32_bf16 v[92:95], v[142:145], v[198:201], v[92:95]
	v_mfma_f32_16x16x32_bf16 v[88:91], v[150:153], v[198:201], v[88:91]
	v_mfma_f32_16x16x32_bf16 v[72:75], v[150:153], v[206:209], v[72:75]
	v_mfma_f32_16x16x32_bf16 v[76:79], v[142:145], v[206:209], v[76:79]
	v_mfma_f32_16x16x32_bf16 v[124:127], v[146:149], v[178:181], v[124:127]
	v_mfma_f32_16x16x32_bf16 v[120:123], v[154:157], v[178:181], v[120:123]
	v_mfma_f32_16x16x32_bf16 v[104:107], v[154:157], v[186:189], v[104:107]
	v_mfma_f32_16x16x32_bf16 v[108:111], v[146:149], v[186:189], v[108:111]
	v_mfma_f32_16x16x32_bf16 v[92:95], v[146:149], v[202:205], v[92:95]
	v_mfma_f32_16x16x32_bf16 v[88:91], v[154:157], v[202:205], v[88:91]
	v_mfma_f32_16x16x32_bf16 v[72:75], v[154:157], v[210:213], v[72:75]
	v_mfma_f32_16x16x32_bf16 v[76:79], v[146:149], v[210:213], v[76:79]
	s_setprio 0
	s_setprio 1
	v_mfma_f32_16x16x32_bf16 v[116:119], v[158:161], v[174:177], v[116:119]
	v_mfma_f32_16x16x32_bf16 v[112:115], v[166:169], v[174:177], v[112:115]
	v_mfma_f32_16x16x32_bf16 v[96:99], v[166:169], v[182:185], v[96:99]
	v_mfma_f32_16x16x32_bf16 v[100:103], v[158:161], v[182:185], v[100:103]
	v_mfma_f32_16x16x32_bf16 v[84:87], v[158:161], v[198:201], v[84:87]
	v_mfma_f32_16x16x32_bf16 v[80:83], v[166:169], v[198:201], v[80:83]
	v_mfma_f32_16x16x32_bf16 v[64:67], v[166:169], v[206:209], v[64:67]
	v_mfma_f32_16x16x32_bf16 v[68:71], v[158:161], v[206:209], v[68:71]
	v_mfma_f32_16x16x32_bf16 v[116:119], v[162:165], v[178:181], v[116:119]
	v_mfma_f32_16x16x32_bf16 v[112:115], v[170:173], v[178:181], v[112:115]
	v_mfma_f32_16x16x32_bf16 v[96:99], v[170:173], v[186:189], v[96:99]
	v_mfma_f32_16x16x32_bf16 v[100:103], v[162:165], v[186:189], v[100:103]
	v_mfma_f32_16x16x32_bf16 v[84:87], v[162:165], v[202:205], v[84:87]
	v_mfma_f32_16x16x32_bf16 v[80:83], v[170:173], v[202:205], v[80:83]
	v_mfma_f32_16x16x32_bf16 v[64:67], v[170:173], v[210:213], v[64:67]
	v_mfma_f32_16x16x32_bf16 v[68:71], v[162:165], v[210:213], v[68:71]
	s_setprio 0
	s_barrier
	s_add_i32 s42, s59, s3
	v_lshl_add_u64 v[190:191], v[190:191], 0, s[8:9]
	s_mov_b32 m0, s42
	ds_read_b128 v[174:177], v197 offset:49152
	ds_read_b128 v[178:181], v197 offset:50176
	ds_read_b128 v[182:185], v197 offset:51200
	ds_read_b128 v[186:189], v197 offset:52224
	ds_read_b128 v[198:201], v197 offset:53248
	ds_read_b128 v[202:205], v197 offset:54272
	ds_read_b128 v[206:209], v197 offset:55296
	ds_read_b128 v[210:213], v197 offset:56320
	global_load_lds_dwordx4 v[190:191], off
	s_add_i32 m0, s42, 0x2000
	s_add_u32 s40, s40, 0x100080
	v_lshl_add_u64 v[190:191], v[214:215], 0, s[8:9]
	s_addc_u32 s41, s41, 0
	s_add_i32 s42, s62, s3
	global_load_lds_dwordx4 v[190:191], off
	v_lshl_add_u64 v[190:191], s[40:41], 0, v[128:129]
	s_mov_b32 m0, s42
	s_nop 0
	global_load_lds_dwordx4 v[190:191], off
	v_lshl_add_u64 v[190:191], s[40:41], 0, v[130:131]
	s_add_i32 m0, s42, 0x2000
	s_nop 0
	global_load_lds_dwordx4 v[190:191], off
	v_lshl_add_u64 v[190:191], v[216:217], 0, s[8:9]
	s_mov_b32 m0, s44
	s_nop 0
	global_load_lds_dwordx4 v[190:191], off
	v_lshl_add_u64 v[190:191], v[218:219], 0, s[8:9]
	s_mov_b32 m0, s45
	s_nop 0
	global_load_lds_dwordx4 v[190:191], off
	s_waitcnt vmcnt(8)
	s_waitcnt lgkmcnt(0)
	s_barrier
	s_setprio 1
	s_waitcnt lgkmcnt(0)
	v_mfma_f32_16x16x32_bf16 v[60:63], v[142:145], v[174:177], v[60:63]
	v_mfma_f32_16x16x32_bf16 v[56:59], v[150:153], v[174:177], v[56:59]
	v_mfma_f32_16x16x32_bf16 v[40:43], v[150:153], v[182:185], v[40:43]
	v_mfma_f32_16x16x32_bf16 v[44:47], v[142:145], v[182:185], v[44:47]
	v_mfma_f32_16x16x32_bf16 v[28:31], v[142:145], v[198:201], v[28:31]
	v_mfma_f32_16x16x32_bf16 v[24:27], v[150:153], v[198:201], v[24:27]
	v_mfma_f32_16x16x32_bf16 v[8:11], v[150:153], v[206:209], v[8:11]
	v_mfma_f32_16x16x32_bf16 v[12:15], v[142:145], v[206:209], v[12:15]
	v_mfma_f32_16x16x32_bf16 v[60:63], v[146:149], v[178:181], v[60:63]
	v_mfma_f32_16x16x32_bf16 v[56:59], v[154:157], v[178:181], v[56:59]
	v_mfma_f32_16x16x32_bf16 v[40:43], v[154:157], v[186:189], v[40:43]
	v_mfma_f32_16x16x32_bf16 v[44:47], v[146:149], v[186:189], v[44:47]
	v_mfma_f32_16x16x32_bf16 v[28:31], v[146:149], v[202:205], v[28:31]
	v_mfma_f32_16x16x32_bf16 v[24:27], v[154:157], v[202:205], v[24:27]
	v_mfma_f32_16x16x32_bf16 v[8:11], v[154:157], v[210:213], v[8:11]
	v_mfma_f32_16x16x32_bf16 v[12:15], v[146:149], v[210:213], v[12:15]
	s_setprio 0
	s_setprio 1
	v_mfma_f32_16x16x32_bf16 v[52:55], v[158:161], v[174:177], v[52:55]
	v_mfma_f32_16x16x32_bf16 v[48:51], v[166:169], v[174:177], v[48:51]
	v_mfma_f32_16x16x32_bf16 v[32:35], v[166:169], v[182:185], v[32:35]
	v_mfma_f32_16x16x32_bf16 v[36:39], v[158:161], v[182:185], v[36:39]
	v_mfma_f32_16x16x32_bf16 v[20:23], v[158:161], v[198:201], v[20:23]
	v_mfma_f32_16x16x32_bf16 v[16:19], v[166:169], v[198:201], v[16:19]
	v_mfma_f32_16x16x32_bf16 v[0:3], v[166:169], v[206:209], v[0:3]
	v_mfma_f32_16x16x32_bf16 v[4:7], v[158:161], v[206:209], v[4:7]
	v_mfma_f32_16x16x32_bf16 v[52:55], v[162:165], v[178:181], v[52:55]
	v_mfma_f32_16x16x32_bf16 v[48:51], v[170:173], v[178:181], v[48:51]
	v_mfma_f32_16x16x32_bf16 v[32:35], v[170:173], v[186:189], v[32:35]
	v_mfma_f32_16x16x32_bf16 v[36:39], v[162:165], v[186:189], v[36:39]
	v_mfma_f32_16x16x32_bf16 v[20:23], v[162:165], v[202:205], v[20:23]
	v_mfma_f32_16x16x32_bf16 v[16:19], v[170:173], v[202:205], v[16:19]
	v_mfma_f32_16x16x32_bf16 v[0:3], v[170:173], v[210:213], v[0:3]
	v_mfma_f32_16x16x32_bf16 v[4:7], v[162:165], v[210:213], v[4:7]
	s_setprio 0
	s_barrier
	s_add_i32 s58, s58, 2
	s_add_u32 s38, s38, 0x100
	s_addc_u32 s39, s39, 0
	s_add_u32 s56, s56, 0x100
	s_addc_u32 s57, s57, 0
	s_cmp_gt_u32 s58, 61
	s_cbranch_scc0 .LBB0_828
	s_and_b64 vcc, exec, s[10:11]
	s_cbranch_vccz .LBB0_831
	s_barrier
